# P2 power-phase interleave, light form: 25 parked SGPRs, NA-first guard load issued at the top of the NA epilogue and tested before its first store
# baseline (speedup 1.0000x reference)
; __global__ void __launch_bounds__(NWAVES * 64, 2) mega_fwd(Args args) {
;     ...
;         for (int u = vcu; u < BATCH * NHEAD * 16; u += G) {
;             const int bh = u >> 4, qb = u & 15;
;             datt::diff_unit2<8>(PROJ, KBI, VBI, out, MIX, subg, lam, bh >> 3, bh & 7, qb, (char*)lds + RING_OFF, SJ, (const unsigned*)(ctl + CW_P1D), (G == 256 && N_LAUNCHES != PER_PHASE) ? 256u : 0u);
;         }
;         for (int u = vcu; u < BATCH * NHEAD * 16; u += G) {
;             const int bh = u >> 4, rg = u & 15;
;             att::na_unit<0>(PROJ, MIX, relb, bh >> 3, bh & 7, rg, (char*)lds + RING_OFF);
;         }
.Lp2_nafirst:
	v_writelane_b32 v243, s8, 0
	v_writelane_b32 v243, s9, 1
	v_writelane_b32 v243, s10, 2
	v_writelane_b32 v243, s11, 3
	v_writelane_b32 v243, s14, 4
	v_writelane_b32 v243, s15, 5
	v_writelane_b32 v243, s16, 6
	v_writelane_b32 v243, s17, 7
	v_writelane_b32 v243, s18, 8
	v_writelane_b32 v243, s19, 9
	v_writelane_b32 v243, s20, 10
	v_writelane_b32 v243, s21, 11
	v_writelane_b32 v243, s22, 12
	v_writelane_b32 v243, s23, 13
	v_writelane_b32 v243, s33, 14
	v_writelane_b32 v243, s52, 15
	v_writelane_b32 v243, s58, 16
	v_writelane_b32 v243, s59, 17
	v_writelane_b32 v243, s60, 18
	v_writelane_b32 v243, s61, 19
	v_writelane_b32 v243, s62, 20
	v_writelane_b32 v243, s63, 21
	v_writelane_b32 v243, s64, 22
	v_writelane_b32 v243, s65, 23
	v_writelane_b32 v242, 1, 62
	s_branch .Lp2_na_entry
.Lp2_after_na:
	v_readlane_b32 s8, v243, 0
	v_readlane_b32 s9, v243, 1
	v_readlane_b32 s10, v243, 2
	v_readlane_b32 s11, v243, 3
	v_readlane_b32 s14, v243, 4
	v_readlane_b32 s15, v243, 5
	v_readlane_b32 s16, v243, 6
	v_readlane_b32 s17, v243, 7
	v_readlane_b32 s18, v243, 8
	v_readlane_b32 s19, v243, 9
	v_readlane_b32 s20, v243, 10
	v_readlane_b32 s21, v243, 11
	v_readlane_b32 s22, v243, 12
	v_readlane_b32 s23, v243, 13
	v_readlane_b32 s33, v243, 14
	v_readlane_b32 s52, v243, 15
	v_readlane_b32 s58, v243, 16
	v_readlane_b32 s59, v243, 17
	v_readlane_b32 s60, v243, 18
	v_readlane_b32 s61, v243, 19
	v_readlane_b32 s62, v243, 20
	v_readlane_b32 s63, v243, 21
	v_readlane_b32 s64, v243, 22
	v_readlane_b32 s65, v243, 23
	s_nop 3
	v_writelane_b32 v242, 2, 62
	s_branch .Lp2_diff_entry

; __device__ __forceinline__ int crow(int r, int hi) { return (r & 3) + 8 * (r >> 2) + 4 * hi; }
; __device__ __forceinline__ unsigned cvtpk(float lo, float hi) { unsigned r; asm volatile("v_cvt_pk_bf16_f32 %0, %1, %2" : "=v"(r) : "v"(lo), "v"(hi)); return r; }
; template <int VAR> __device__ __forceinline__ void na_unit(const bf16* __restrict__ proj, bf16* mix, const float* __restrict__ relb, int b, int h, int rg, char* lds) {
;     ...
;   if (hi == 0) li_l[r32] = l_reg; asm volatile("s_waitcnt lgkmcnt(0)" ::: "memory");
;   float rli[16];
; #pragma unroll
;   for (int r = 0; r < 16; ++r) rli[r] = __builtin_amdgcn_rcpf(li_l[crow(r, hi)]);
;   bf16* stg = (bf16*)(lds + wid * 8192);
; #pragma unroll
;   for (int r = 0; r < 16; ++r) { const int orow = crow(r, hi);
; #pragma unroll
;     for (int d0 = 0; d0 < 4; ++d0) stg[orow * 128 + d0 * 32 + r32] = (bf16)(cvtpk(o[d0][r] * rli[r], 0.f) & 0xffffu); }
; template <int THRL> ...
;     ...
;       const unsigned gd_ = need ? __hip_atomic_load(guard, __ATOMIC_RELAXED, __HIP_MEMORY_SCOPE_AGENT) : 0u;
.LBB0_507:
	s_or_b64 exec, exec, s[4:5]
	v_readlane_b32 s98, v242, 62
	s_cmp_eq_u32 s98, 1
	s_cbranch_scc0 .Lna_gd_skip1
	s_add_u32 s98, s70, 0xe014100
	s_addc_u32 s99, s71, 0
	v_mov_b32_e32 v245, 0
	global_load_dword v244, v245, s[98:99] sc1
.Lna_gd_skip1:
	s_waitcnt lgkmcnt(0)
	v_lshl_add_u32 v10, v167, 2, s82
	ds_read_b128 v[2:5], v10
	ds_read_b128 v[6:9], v10 offset:32
	v_lshlrev_b32_e32 v83, 10, v161
	s_or_b32 s0, s96, s0
	s_lshl_b32 s2, s97, 7
	s_waitcnt lgkmcnt(1)
	v_rcp_f32_e32 v11, v2
	v_rcp_f32_e32 v12, v3
	v_rcp_f32_e32 v13, v4
	v_rcp_f32_e32 v14, v5
	s_waitcnt lgkmcnt(0)
	v_rcp_f32_e32 v15, v6
	ds_read_b128 v[2:5], v10 offset:64
	v_rcp_f32_e32 v16, v7
	v_rcp_f32_e32 v17, v8
	v_rcp_f32_e32 v82, v9
	ds_read_b128 v[6:9], v10 offset:96
	v_lshlrev_b32_e32 v10, 1, v160
	v_add3_u32 v10, s58, v10, v83
	v_mul_f32_e32 v66, v66, v11
	v_mul_f32_e32 v50, v50, v11
	v_mul_f32_e32 v34, v34, v11
	v_mul_f32_e32 v11, v18, v11
	v_cvt_pk_bf16_f32 v66, v66, v147
	ds_write_b16 v10, v66
	v_cvt_pk_bf16_f32 v50, v50, v147
	ds_write_b16 v10, v50 offset:64
	v_cvt_pk_bf16_f32 v34, v34, v147
	ds_write_b16 v10, v34 offset:128
	v_cvt_pk_bf16_f32 v11, v11, v147
	ds_write_b16 v10, v11 offset:192
	v_mul_f32_e32 v11, v67, v12
	v_cvt_pk_bf16_f32 v11, v11, v147
	ds_write_b16 v10, v11 offset:256
	v_mul_f32_e32 v11, v51, v12
	v_cvt_pk_bf16_f32 v11, v11, v147
	ds_write_b16 v10, v11 offset:320
	v_mul_f32_e32 v11, v35, v12
	v_cvt_pk_bf16_f32 v11, v11, v147
	ds_write_b16 v10, v11 offset:384
	v_mul_f32_e32 v11, v19, v12
	v_cvt_pk_bf16_f32 v11, v11, v147
	ds_write_b16 v10, v11 offset:448
	v_mul_f32_e32 v11, v68, v13
	v_cvt_pk_bf16_f32 v11, v11, v147
	ds_write_b16 v10, v11 offset:512
	v_mul_f32_e32 v11, v52, v13
	v_cvt_pk_bf16_f32 v11, v11, v147
	ds_write_b16 v10, v11 offset:576
	v_mul_f32_e32 v11, v36, v13
	v_cvt_pk_bf16_f32 v11, v11, v147
	ds_write_b16 v10, v11 offset:640
	v_mul_f32_e32 v11, v20, v13
	v_cvt_pk_bf16_f32 v11, v11, v147
	ds_write_b16 v10, v11 offset:704
	v_mul_f32_e32 v11, v69, v14
	v_cvt_pk_bf16_f32 v11, v11, v147
	ds_write_b16 v10, v11 offset:768
	v_mul_f32_e32 v11, v53, v14
	v_cvt_pk_bf16_f32 v11, v11, v147
	ds_write_b16 v10, v11 offset:832
	v_mul_f32_e32 v11, v37, v14
	v_cvt_pk_bf16_f32 v11, v11, v147
	ds_write_b16 v10, v11 offset:896
	v_mul_f32_e32 v11, v21, v14
	v_cvt_pk_bf16_f32 v11, v11, v147
	ds_write_b16 v10, v11 offset:960
	v_mul_f32_e32 v11, v70, v15
	v_cvt_pk_bf16_f32 v11, v11, v147
	ds_write_b16 v10, v11 offset:2048
	v_mul_f32_e32 v11, v54, v15
	v_cvt_pk_bf16_f32 v11, v11, v147
	ds_write_b16 v10, v11 offset:2112
	v_mul_f32_e32 v11, v38, v15
	v_cvt_pk_bf16_f32 v11, v11, v147
	ds_write_b16 v10, v11 offset:2176
	v_mul_f32_e32 v11, v22, v15
	v_cvt_pk_bf16_f32 v11, v11, v147
	ds_write_b16 v10, v11 offset:2240
	v_mul_f32_e32 v11, v71, v16
	v_cvt_pk_bf16_f32 v11, v11, v147
	ds_write_b16 v10, v11 offset:2304
	v_mul_f32_e32 v11, v55, v16
	v_cvt_pk_bf16_f32 v11, v11, v147
	ds_write_b16 v10, v11 offset:2368
	v_mul_f32_e32 v11, v39, v16
	v_cvt_pk_bf16_f32 v11, v11, v147
	ds_write_b16 v10, v11 offset:2432
	v_mul_f32_e32 v11, v23, v16
	v_cvt_pk_bf16_f32 v11, v11, v147
	ds_write_b16 v10, v11 offset:2496
	v_mul_f32_e32 v11, v72, v17
	v_cvt_pk_bf16_f32 v11, v11, v147
	ds_write_b16 v10, v11 offset:2560
	v_mul_f32_e32 v11, v56, v17
	v_cvt_pk_bf16_f32 v11, v11, v147
	ds_write_b16 v10, v11 offset:2624
	v_mul_f32_e32 v11, v40, v17
	v_cvt_pk_bf16_f32 v11, v11, v147
	ds_write_b16 v10, v11 offset:2688
	v_mul_f32_e32 v11, v24, v17
	v_cvt_pk_bf16_f32 v11, v11, v147
	ds_write_b16 v10, v11 offset:2752
	v_mul_f32_e32 v11, v73, v82
	v_cvt_pk_bf16_f32 v11, v11, v147
	ds_write_b16 v10, v11 offset:2816
	v_mul_f32_e32 v11, v57, v82
	v_cvt_pk_bf16_f32 v11, v11, v147
	s_waitcnt lgkmcnt(14)
; __device__ __forceinline__ int crow(int r, int hi) { return (r & 3) + 8 * (r >> 2) + 4 * hi; }
; __device__ __forceinline__ unsigned cvtpk(float lo, float hi) { unsigned r; asm volatile("v_cvt_pk_bf16_f32 %0, %1, %2" : "=v"(r) : "v"(lo), "v"(hi)); return r; }
; __device__ __forceinline__ void st16_wt(void* p, u32x4 v) { asm volatile("global_store_dwordx4 %0, %1, off sc1\n\ts_nop 1" :: "v"(p), "v"(v) : "memory"); }
; template <int VAR> __device__ __forceinline__ void na_unit(const bf16* __restrict__ proj, bf16* mix, const float* __restrict__ relb, int b, int h, int rg, char* lds) {
;     ...
;   for (int r = 0; r < 16; ++r) { const int orow = crow(r, hi);
; #pragma unroll
;     for (int d0 = 0; d0 < 4; ++d0) stg[orow * 128 + d0 * 32 + r32] = (bf16)(cvtpk(o[d0][r] * rli[r], 0.f) & 0xffffu); }
;   asm volatile("s_waitcnt lgkmcnt(0)" ::: "memory");
;   bf16* Mw = mix + (tok0 + gr * 64 + 32 * (wid & 1)) * 2048 + 1024 + h * 128;
; #pragma unroll
;   for (int i = 0; i < 8; ++i) { const int row = i * 4 + (lane >> 4), ch = lane & 15;
;     const u32x4 v = *(const u32x4*)(stg + row * 128 + ch * 8); st16_wt(Mw + (long)row * 2048 + ch * 8, v); }
; template <int THRL> ...
;     ...
;       if (gd_ < need) { unsigned sp_ = 0u; while (__hip_atomic_load(guard, __ATOMIC_RELAXED, __HIP_MEMORY_SCOPE_AGENT) < need && ++sp_ < (1u << 22)) __builtin_amdgcn_s_sleep(2); }
	v_rcp_f32_e32 v2, v2
	ds_write_b16 v10, v11 offset:2880
	v_mul_f32_e32 v11, v41, v82
	v_cvt_pk_bf16_f32 v11, v11, v147
	ds_write_b16 v10, v11 offset:2944
	v_mul_f32_e32 v11, v25, v82
	v_cvt_pk_bf16_f32 v11, v11, v147
	ds_write_b16 v10, v11 offset:3008
	v_mul_f32_e32 v11, v74, v2
	v_cvt_pk_bf16_f32 v11, v11, v147
	v_rcp_f32_e32 v3, v3
	ds_write_b16 v10, v11 offset:4096
	v_mul_f32_e32 v11, v58, v2
	v_cvt_pk_bf16_f32 v11, v11, v147
	ds_write_b16 v10, v11 offset:4160
	v_mul_f32_e32 v11, v42, v2
	v_mul_f32_e32 v2, v26, v2
	v_cvt_pk_bf16_f32 v11, v11, v147
	ds_write_b16 v10, v11 offset:4224
	v_cvt_pk_bf16_f32 v2, v2, v147
	ds_write_b16 v10, v2 offset:4288
	v_mul_f32_e32 v2, v75, v3
	v_cvt_pk_bf16_f32 v2, v2, v147
	ds_write_b16 v10, v2 offset:4352
	v_mul_f32_e32 v2, v59, v3
	v_cvt_pk_bf16_f32 v2, v2, v147
	v_rcp_f32_e32 v4, v4
	ds_write_b16 v10, v2 offset:4416
	v_mul_f32_e32 v2, v43, v3
	v_cvt_pk_bf16_f32 v2, v2, v147
	ds_write_b16 v10, v2 offset:4480
	v_mul_f32_e32 v2, v27, v3
	v_cvt_pk_bf16_f32 v2, v2, v147
	ds_write_b16 v10, v2 offset:4544
	v_mul_f32_e32 v2, v76, v4
	v_cvt_pk_bf16_f32 v2, v2, v147
	ds_write_b16 v10, v2 offset:4608
	v_mul_f32_e32 v2, v60, v4
	v_cvt_pk_bf16_f32 v2, v2, v147
	v_rcp_f32_e32 v5, v5
	ds_write_b16 v10, v2 offset:4672
	v_mul_f32_e32 v2, v44, v4
	v_cvt_pk_bf16_f32 v2, v2, v147
	ds_write_b16 v10, v2 offset:4736
	v_mul_f32_e32 v2, v28, v4
	v_cvt_pk_bf16_f32 v2, v2, v147
	ds_write_b16 v10, v2 offset:4800
	v_mul_f32_e32 v2, v77, v5
	v_cvt_pk_bf16_f32 v2, v2, v147
	ds_write_b16 v10, v2 offset:4864
	v_mul_f32_e32 v2, v61, v5
	v_cvt_pk_bf16_f32 v2, v2, v147
	v_rcp_f32_e32 v6, v6
	ds_write_b16 v10, v2 offset:4928
	v_mul_f32_e32 v2, v45, v5
	v_cvt_pk_bf16_f32 v2, v2, v147
	ds_write_b16 v10, v2 offset:4992
	v_mul_f32_e32 v2, v29, v5
	v_cvt_pk_bf16_f32 v2, v2, v147
	ds_write_b16 v10, v2 offset:5056
	v_mul_f32_e32 v2, v78, v6
	v_cvt_pk_bf16_f32 v2, v2, v147
	ds_write_b16 v10, v2 offset:6144
	v_mul_f32_e32 v2, v62, v6
	v_cvt_pk_bf16_f32 v2, v2, v147
	v_rcp_f32_e32 v7, v7
	ds_write_b16 v10, v2 offset:6208
	v_mul_f32_e32 v2, v46, v6
	v_cvt_pk_bf16_f32 v2, v2, v147
	ds_write_b16 v10, v2 offset:6272
	v_mul_f32_e32 v2, v30, v6
	v_cvt_pk_bf16_f32 v2, v2, v147
	ds_write_b16 v10, v2 offset:6336
	v_mul_f32_e32 v2, v79, v7
	v_cvt_pk_bf16_f32 v2, v2, v147
	ds_write_b16 v10, v2 offset:6400
	v_mul_f32_e32 v2, v63, v7
	v_cvt_pk_bf16_f32 v2, v2, v147
	v_rcp_f32_e32 v8, v8
	ds_write_b16 v10, v2 offset:6464
	v_mul_f32_e32 v2, v47, v7
	v_cvt_pk_bf16_f32 v2, v2, v147
	ds_write_b16 v10, v2 offset:6528
	v_mul_f32_e32 v2, v31, v7
	v_cvt_pk_bf16_f32 v2, v2, v147
	ds_write_b16 v10, v2 offset:6592
	v_mul_f32_e32 v2, v80, v8
	v_cvt_pk_bf16_f32 v2, v2, v147
	ds_write_b16 v10, v2 offset:6656
	v_mul_f32_e32 v2, v64, v8
	v_cvt_pk_bf16_f32 v2, v2, v147
	v_rcp_f32_e32 v9, v9
	ds_write_b16 v10, v2 offset:6720
	v_mul_f32_e32 v2, v48, v8
	v_cvt_pk_bf16_f32 v2, v2, v147
	ds_write_b16 v10, v2 offset:6784
	v_mul_f32_e32 v2, v32, v8
	v_cvt_pk_bf16_f32 v2, v2, v147
	ds_write_b16 v10, v2 offset:6848
	v_mul_f32_e32 v2, v81, v9
	v_cvt_pk_bf16_f32 v2, v2, v147
	ds_write_b16 v10, v2 offset:6912
	v_mul_f32_e32 v2, v65, v9
	v_cvt_pk_bf16_f32 v2, v2, v147
	s_lshl_b64 s[0:1], s[0:1], 12
	ds_write_b16 v10, v2 offset:6976
	v_mul_f32_e32 v2, v49, v9
	s_add_u32 s0, s92, s0
	v_cvt_pk_bf16_f32 v2, v2, v147
	s_addc_u32 s1, s93, s1
	s_lshl_b32 s2, s2, 1
	ds_write_b16 v10, v2 offset:7040
	v_mul_f32_e32 v2, v33, v9
	s_add_u32 s0, s0, s2
	v_cvt_pk_bf16_f32 v2, v2, v147
	ds_write_b16 v10, v2 offset:7104
	s_addc_u32 s1, s1, 0
	v_lshrrev_b32_e32 v10, 4, v149
	v_mov_b32_e32 v149, v147
	v_lshl_add_u64 v[6:7], s[0:1], 0, v[148:149]
	s_mov_b64 s[0:1], 0x800
	v_lshl_add_u32 v11, v151, 1, s58
	v_lshl_add_u64 v[6:7], v[6:7], 0, s[0:1]
	v_lshlrev_b32_e32 v146, 12, v10
	s_waitcnt lgkmcnt(0)
	v_lshl_add_u32 v2, v10, 8, v11
	v_lshl_add_u64 v[8:9], v[6:7], 0, v[146:147]
	ds_read_b128 v[2:5], v2
	s_waitcnt lgkmcnt(0)
	v_readlane_b32 s100, v242, 62
	s_cmp_eq_u32 s100, 1
	s_cbranch_scc0 .Lna_gd_done
	s_mov_b32 s100, 0
.Lna_gd_spin:
	s_waitcnt vmcnt(0)
	v_readfirstlane_b32 s101, v244
	s_cmp_ge_u32 s101, 0x100
	s_cbranch_scc1 .Lna_gd_done
	s_add_i32 s100, s100, 1
	s_cmp_lt_u32 s100, 0x100000
	s_cbranch_scc0 .Lna_gd_done
	global_load_dword v244, v245, s[98:99] sc1
	s_branch .Lna_gd_spin
.Lna_gd_done:
	global_store_dwordx4 v[8:9], v[2:5], off sc1
	s_nop 1
	v_or_b32_e32 v8, 4, v10
	v_lshlrev_b32_e32 v146, 12, v8
	v_lshl_add_u32 v2, v8, 8, v11
	v_lshl_add_u64 v[8:9], v[6:7], 0, v[146:147]
	ds_read_b128 v[2:5], v2
	s_waitcnt lgkmcnt(0)
	global_store_dwordx4 v[8:9], v[2:5], off sc1
	s_nop 1
	v_or_b32_e32 v8, 8, v10
	v_lshlrev_b32_e32 v146, 12, v8
	v_lshl_add_u32 v2, v8, 8, v11
	v_lshl_add_u64 v[8:9], v[6:7], 0, v[146:147]
	ds_read_b128 v[2:5], v2
	s_waitcnt lgkmcnt(0)
	global_store_dwordx4 v[8:9], v[2:5], off sc1
	s_nop 1
	v_or_b32_e32 v8, 12, v10
	v_lshlrev_b32_e32 v146, 12, v8
	v_lshl_add_u32 v2, v8, 8, v11
	v_lshl_add_u64 v[8:9], v[6:7], 0, v[146:147]
	ds_read_b128 v[2:5], v2
	s_waitcnt lgkmcnt(0)
	global_store_dwordx4 v[8:9], v[2:5], off sc1
	s_nop 1
	v_or_b32_e32 v8, 16, v10
	v_lshlrev_b32_e32 v146, 12, v8
	v_lshl_add_u32 v2, v8, 8, v11
	v_lshl_add_u64 v[8:9], v[6:7], 0, v[146:147]
	ds_read_b128 v[2:5], v2
	s_waitcnt lgkmcnt(0)
	global_store_dwordx4 v[8:9], v[2:5], off sc1
	s_nop 1
	v_or_b32_e32 v8, 20, v10
	v_lshlrev_b32_e32 v146, 12, v8
	v_lshl_add_u32 v2, v8, 8, v11
	v_lshl_add_u64 v[8:9], v[6:7], 0, v[146:147]
	ds_read_b128 v[2:5], v2
	s_waitcnt lgkmcnt(0)
	global_store_dwordx4 v[8:9], v[2:5], off sc1
	s_nop 1
	v_or_b32_e32 v8, 24, v10
	v_lshlrev_b32_e32 v146, 12, v8
	v_lshl_add_u32 v2, v8, 8, v11
	v_lshl_add_u64 v[8:9], v[6:7], 0, v[146:147]
	ds_read_b128 v[2:5], v2
	s_waitcnt lgkmcnt(0)
	global_store_dwordx4 v[8:9], v[2:5], off sc1
	s_nop 1
	v_or_b32_e32 v8, 28, v10
	v_lshl_add_u32 v2, v8, 8, v11
	v_lshlrev_b32_e32 v146, 12, v8
	ds_read_b128 v[2:5], v2
	v_lshl_add_u64 v[6:7], v[6:7], 0, v[146:147]
	s_waitcnt lgkmcnt(0)
	global_store_dwordx4 v[6:7], v[2:5], off sc1
	s_nop 1
	s_add_i32 s89, s89, s33
	s_add_i32 s3, s3, s50
	s_cmpk_gt_i32 s89, 0xff
	s_cbranch_scc1 .LBB0_574
